# 2b first-item remap guarded by gridDim==512 (falls back to the original item order otherwise), padded to keep code placement
# baseline (speedup 1.0000x reference)
; __global__ void __launch_bounds__(256, 2) mega(Params p) {
;     ...
;     for (int rep = 0; rep < REP_2B; ++rep) {
;       bool first = true;
;       for (;;) {
;         int it;
;         if (first) { it = (int)blockIdx.x; first = false; }
;         else it = next_item(ctr + layer * 2 + 1 + 8 * rep, &slot) + (int)gridDim.x;
;         if (rep > 0) { it += PROBE_2B_LO; if (it >= PROBE_2B_HI) break; }
;         if (it >= 288 + 192 + 24 + 256 + 1536) break;
;         it = (it < 192) ? (it + 384) : ((it < 480) ? (it - 192) : ((it < 504) ? (it + 608) : ((it < 760) ? (it + 328) : (it + 352))));
.LBB0_354:
	s_or_b64 exec, exec, s[0:1]
	s_mul_i32 s0, s69, 12
	v_writelane_b32 v255, s0, 51
	v_readlane_b32 s2, v252, 0
	s_waitcnt lgkmcnt(0)
	s_barrier
	s_nop 0
	s_nop 0
	s_nop 0
	s_nop 0
	s_nop 0
	s_nop 0
	s_nop 0
	s_nop 0
	s_nop 0
	s_nop 0
	s_nop 0
	v_readlane_b32 s98, v255, 38
	s_cmp_eq_u32 s98, 0x200
	s_cbranch_scc0 .Lmap2b_done
	s_cmp_lt_u32 s2, 192
	s_cbranch_scc1 .Lmap2b_done
	s_cmp_lt_u32 s2, 224
	s_cbranch_scc0 .Lmap2b_a
	s_add_i32 s2, s2, 128
	s_branch .Lmap2b_done
